# prologue w_in transposes: the 16 norm-weight scales per item requested together instead of one at a time behind full drains
# speedup vs baseline: 1.0454x; 1.0047x over previous
; #define LAS __attribute__((address_space(3)))
; __device__ __forceinline__ unsigned pk2(float lo, float hi) { return f2bf(lo) | (f2bf(hi) << 16); }
; __device__ __forceinline__ void p0_transpose_item(const float* W, int K, int N, bf16* WT, LAS float* scr_f, int item, int lane, const float* kscale = nullptr) {
;     LAS bf16* scr = (LAS bf16*)scr_f;
;     const int nblk = N / 64, kb = item / nblk, nb = item % nblk, k0 = 64 * kb, n0 = 64 * nb;
;     f32x4 v[16];
; #pragma unroll
;     for (int i = 0; i < 16; ++i) v[i] = __builtin_nontemporal_load((const f32x4*)(W + (size_t)(k0 + 4 * i + (lane >> 4)) * N + n0 + (lane & 15) * 4));
; #pragma unroll
;     for (int i = 0; i < 16; ++i) { const float sc = kscale ? kscale[k0 + 4 * i + (lane >> 4)] : 1.0f;
;         *(LAS v2u*)(scr + (4 * i + (lane >> 4)) * 68 + (lane & 15) * 4) = (v2u){pk2(v[i].x * sc, v[i].y * sc), pk2(v[i].z * sc, v[i].w * sc)}; }
; __device__ __forceinline__ void prologue(const Args& a, LAS unsigned char* lds, int vcu, int G, int wave, int lane) {
;     ...
;         if (r < I_IN) { p0_transpose_item(a.in[2] + (size_t)l * D * DIN, D, DIN, (bf16*)(ws + WS_WIN) + (size_t)l * DIN * D, scr, r, lane, a.in[1] + (size_t)l * D); continue; } r -= I_IN;
.LBB0_20:
	s_andn2_b64 vcc, exec, s[2:3]
	s_cbranch_vccnz .LBB0_13
	s_mul_i32 s3, s46, 0xe00000
	s_mul_hi_i32 s2, s46, 0xe00000
	s_add_u32 s6, s24, s3
	s_addc_u32 s49, s25, s2
	s_lshl_b64 s[2:3], s[46:47], 12
	s_add_u32 s86, s22, s2
	s_mul_hi_i32 s2, s4, 0x92492493
	s_addc_u32 s87, s23, s3
	s_add_i32 s2, s2, s4
	s_lshr_b32 s3, s2, 31
	s_ashr_i32 s2, s2, 5
	s_add_i32 s2, s2, s3
	s_mul_i32 s3, s2, 56
	s_sub_i32 s3, s4, s3
	s_lshl_b32 s48, s2, 6
	s_lshl_b32 s2, s3, 6
	s_ashr_i32 s3, s2, 31
	s_lshl_b64 s[4:5], s[2:3], 2
	s_add_u32 s4, s6, s4
	v_or_b32_e32 v70, s48, v73
	s_addc_u32 s5, s49, s5
	v_lshl_add_u64 v[2:3], s[4:5], 0, v[66:67]
	v_or_b32_e32 v6, 4, v70
	v_mad_i64_i32 v[4:5], s[4:5], v70, s82, v[2:3]
	v_mad_i64_i32 v[6:7], s[4:5], v6, s82, v[2:3]
	global_load_dwordx4 v[62:65], v[4:5], off nt
	global_load_dwordx4 v[58:61], v[6:7], off nt
	v_or_b32_e32 v4, 8, v70
	v_or_b32_e32 v6, 12, v70
	v_mad_i64_i32 v[4:5], s[4:5], v4, s82, v[2:3]
	v_mad_i64_i32 v[6:7], s[4:5], v6, s82, v[2:3]
	global_load_dwordx4 v[54:57], v[4:5], off nt
	global_load_dwordx4 v[50:53], v[6:7], off nt
	v_or_b32_e32 v4, 16, v70
	v_or_b32_e32 v6, 20, v70
	v_mad_i64_i32 v[4:5], s[4:5], v4, s82, v[2:3]
	v_mad_i64_i32 v[6:7], s[4:5], v6, s82, v[2:3]
	global_load_dwordx4 v[46:49], v[4:5], off nt
	global_load_dwordx4 v[42:45], v[6:7], off nt
	v_or_b32_e32 v4, 24, v70
	v_or_b32_e32 v6, 28, v70
	v_mad_i64_i32 v[4:5], s[4:5], v4, s82, v[2:3]
	v_mad_i64_i32 v[6:7], s[4:5], v6, s82, v[2:3]
	global_load_dwordx4 v[38:41], v[4:5], off nt
	global_load_dwordx4 v[34:37], v[6:7], off nt
	v_or_b32_e32 v4, 32, v70
	v_or_b32_e32 v6, 36, v70
	v_mad_i64_i32 v[4:5], s[4:5], v4, s82, v[2:3]
	v_mad_i64_i32 v[6:7], s[4:5], v6, s82, v[2:3]
	v_or_b32_e32 v12, 56, v70
	global_load_dwordx4 v[30:33], v[4:5], off nt
	global_load_dwordx4 v[26:29], v[6:7], off nt
	v_or_b32_e32 v4, 40, v70
	v_or_b32_e32 v6, 44, v70
	v_or_b32_e32 v8, 48, v70
	v_or_b32_e32 v10, 52, v70
	v_mad_i64_i32 v[90:91], s[4:5], v12, s82, v[2:3]
	v_or_b32_e32 v12, 60, v70
	v_mad_i64_i32 v[4:5], s[4:5], v4, s82, v[2:3]
	v_mad_i64_i32 v[6:7], s[4:5], v6, s82, v[2:3]
	v_mad_i64_i32 v[8:9], s[4:5], v8, s82, v[2:3]
	v_mad_i64_i32 v[10:11], s[4:5], v10, s82, v[2:3]
	v_mad_i64_i32 v[2:3], s[4:5], v12, s82, v[2:3]
	global_load_dwordx4 v[22:25], v[4:5], off nt
	global_load_dwordx4 v[18:21], v[6:7], off nt
	global_load_dwordx4 v[14:17], v[8:9], off nt
	s_nop 0
	global_load_dwordx4 v[10:13], v[10:11], off nt
	s_nop 0
	global_load_dwordx4 v[6:9], v[90:91], off nt
	s_nop 0
	global_load_dwordx4 v[2:5], v[2:3], off nt
	v_ashrrev_i32_e32 v71, 31, v70
	v_cndmask_b32_e64 v69, 0, 1, s[44:45]
	v_cmp_ne_u32_e64 s[4:5], 1, v69
	s_andn2_b64 vcc, exec, s[44:45]
	v_lshl_add_u64 v[70:71], v[70:71], 2, s[86:87]
	v_mov_b32_e32 v72, 1.0
	v_mov_b32_e32 v74, 1.0
	s_cbranch_vccnz .LBB0_23
	global_load_dword v74, v[70:71], off
	global_load_dword v93, v[70:71], off offset:16
	global_load_dword v94, v[70:71], off offset:32
	global_load_dword v95, v[70:71], off offset:48
	global_load_dword v96, v[70:71], off offset:64
	global_load_dword v97, v[70:71], off offset:80
	global_load_dword v98, v[70:71], off offset:96
	global_load_dword v99, v[70:71], off offset:112
	global_load_dword v100, v[70:71], off offset:128
	global_load_dword v101, v[70:71], off offset:144
	global_load_dword v102, v[70:71], off offset:160
	global_load_dword v103, v[70:71], off offset:176
	global_load_dword v104, v[70:71], off offset:192
	global_load_dword v105, v[70:71], off offset:208
	global_load_dword v106, v[70:71], off offset:224
	global_load_dword v107, v[70:71], off offset:240
.LBB0_23:
	s_waitcnt vmcnt(15)
	v_mov_b32_e32 v91, v64
	v_mov_b32_e32 v64, v63
	v_mov_b32_e32 v90, v62
	s_waitcnt vmcnt(0)
	v_pk_mul_f32 v[62:63], v[64:65], v[74:75] op_sel_hi:[1,0]
	v_pk_mul_f32 v[90:91], v[90:91], v[74:75] op_sel_hi:[1,0]
	v_and_b32_sdwa v69, v63, v89 dst_sel:DWORD dst_unused:UNUSED_PAD src0_sel:WORD_1 src1_sel:DWORD
	v_and_b32_sdwa v74, v62, v89 dst_sel:DWORD dst_unused:UNUSED_PAD src0_sel:WORD_1 src1_sel:DWORD
	v_and_b32_sdwa v64, v91, v89 dst_sel:DWORD dst_unused:UNUSED_PAD src0_sel:WORD_1 src1_sel:DWORD
	v_and_b32_sdwa v65, v90, v89 dst_sel:DWORD dst_unused:UNUSED_PAD src0_sel:WORD_1 src1_sel:DWORD
	v_add3_u32 v63, v63, v69, s61
	v_add3_u32 v62, v62, v74, s61
	v_add3_u32 v65, v90, v65, s61
	v_add3_u32 v64, v91, v64, s61
	v_and_b32_e32 v63, 0xffff0000, v63
	v_and_b32_e32 v62, 0xffff0000, v62
	v_or_b32_sdwa v63, v63, v64 dst_sel:DWORD dst_unused:UNUSED_PAD src0_sel:DWORD src1_sel:WORD_1
	v_or_b32_sdwa v62, v62, v65 dst_sel:DWORD dst_unused:UNUSED_PAD src0_sel:DWORD src1_sel:WORD_1
	s_and_b64 vcc, exec, s[4:5]
	ds_write_b64 v84, v[62:63]
	s_cbranch_vccnz .LBB0_25
	v_mov_b32_e32 v72, v93
.LBB0_25:
	v_mov_b32_e32 v62, v58
	v_mov_b32_e32 v63, v60
	s_waitcnt vmcnt(0)
	v_pk_mul_f32 v[62:63], v[62:63], v[72:73] op_sel_hi:[1,0]
	v_mov_b32_e32 v60, v59
	v_pk_mul_f32 v[58:59], v[60:61], v[72:73] op_sel_hi:[1,0]
	v_and_b32_sdwa v60, v63, v89 dst_sel:DWORD dst_unused:UNUSED_PAD src0_sel:WORD_1 src1_sel:DWORD
	v_and_b32_sdwa v61, v62, v89 dst_sel:DWORD dst_unused:UNUSED_PAD src0_sel:WORD_1 src1_sel:DWORD
	v_add3_u32 v61, v62, v61, s61
	v_add3_u32 v60, v63, v60, s61
	v_and_b32_sdwa v62, v59, v89 dst_sel:DWORD dst_unused:UNUSED_PAD src0_sel:WORD_1 src1_sel:DWORD
	v_and_b32_sdwa v63, v58, v89 dst_sel:DWORD dst_unused:UNUSED_PAD src0_sel:WORD_1 src1_sel:DWORD
	v_add3_u32 v59, v59, v62, s61
	v_add3_u32 v58, v58, v63, s61
	v_and_b32_e32 v59, 0xffff0000, v59
	v_and_b32_e32 v58, 0xffff0000, v58
	v_or_b32_sdwa v59, v59, v60 dst_sel:DWORD dst_unused:UNUSED_PAD src0_sel:DWORD src1_sel:WORD_1
	v_or_b32_sdwa v58, v58, v61 dst_sel:DWORD dst_unused:UNUSED_PAD src0_sel:DWORD src1_sel:WORD_1
	ds_write_b64 v84, v[58:59] offset:544
	v_mov_b32_e32 v58, 1.0
	s_and_b64 vcc, exec, s[4:5]
	v_mov_b32_e32 v60, 1.0
	s_cbranch_vccnz .LBB0_27
	v_mov_b32_e32 v60, v94
; #define LAS __attribute__((address_space(3)))
; __device__ __forceinline__ unsigned pk2(float lo, float hi) { return f2bf(lo) | (f2bf(hi) << 16); }
; __device__ __forceinline__ void p0_transpose_item(const float* W, int K, int N, bf16* WT, LAS float* scr_f, int item, int lane, const float* kscale = nullptr) {
;     ...
;     for (int i = 0; i < 16; ++i) { const float sc = kscale ? kscale[k0 + 4 * i + (lane >> 4)] : 1.0f;
;         *(LAS v2u*)(scr + (4 * i + (lane >> 4)) * 68 + (lane & 15) * 4) = (v2u){pk2(v[i].x * sc, v[i].y * sc), pk2(v[i].z * sc, v[i].w * sc)}; }
.LBB0_27:
	v_mov_b32_e32 v63, v56
	v_mov_b32_e32 v56, v55
	v_mov_b32_e32 v62, v54
	s_waitcnt vmcnt(0)
	v_pk_mul_f32 v[54:55], v[56:57], v[60:61] op_sel_hi:[1,0]
	v_pk_mul_f32 v[62:63], v[62:63], v[60:61] op_sel_hi:[1,0]
	v_and_b32_sdwa v59, v55, v89 dst_sel:DWORD dst_unused:UNUSED_PAD src0_sel:WORD_1 src1_sel:DWORD
	v_and_b32_sdwa v60, v54, v89 dst_sel:DWORD dst_unused:UNUSED_PAD src0_sel:WORD_1 src1_sel:DWORD
	v_and_b32_sdwa v56, v63, v89 dst_sel:DWORD dst_unused:UNUSED_PAD src0_sel:WORD_1 src1_sel:DWORD
	v_and_b32_sdwa v57, v62, v89 dst_sel:DWORD dst_unused:UNUSED_PAD src0_sel:WORD_1 src1_sel:DWORD
	v_add3_u32 v55, v55, v59, s61
	v_add3_u32 v54, v54, v60, s61
	v_add3_u32 v57, v62, v57, s61
	v_add3_u32 v56, v63, v56, s61
	v_and_b32_e32 v55, 0xffff0000, v55
	v_and_b32_e32 v54, 0xffff0000, v54
	v_or_b32_sdwa v55, v55, v56 dst_sel:DWORD dst_unused:UNUSED_PAD src0_sel:DWORD src1_sel:WORD_1
	v_or_b32_sdwa v54, v54, v57 dst_sel:DWORD dst_unused:UNUSED_PAD src0_sel:DWORD src1_sel:WORD_1
	s_and_b64 vcc, exec, s[4:5]
	ds_write_b64 v84, v[54:55] offset:1088
	s_cbranch_vccnz .LBB0_29
	v_mov_b32_e32 v58, v95
.LBB0_29:
	v_mov_b32_e32 v54, v50
	v_mov_b32_e32 v55, v52
	s_waitcnt vmcnt(0)
	v_pk_mul_f32 v[54:55], v[54:55], v[58:59] op_sel_hi:[1,0]
	v_mov_b32_e32 v52, v51
	v_pk_mul_f32 v[50:51], v[52:53], v[58:59] op_sel_hi:[1,0]
	v_and_b32_sdwa v52, v55, v89 dst_sel:DWORD dst_unused:UNUSED_PAD src0_sel:WORD_1 src1_sel:DWORD
	v_and_b32_sdwa v53, v54, v89 dst_sel:DWORD dst_unused:UNUSED_PAD src0_sel:WORD_1 src1_sel:DWORD
	v_add3_u32 v53, v54, v53, s61
	v_add3_u32 v52, v55, v52, s61
	v_and_b32_sdwa v54, v51, v89 dst_sel:DWORD dst_unused:UNUSED_PAD src0_sel:WORD_1 src1_sel:DWORD
	v_and_b32_sdwa v55, v50, v89 dst_sel:DWORD dst_unused:UNUSED_PAD src0_sel:WORD_1 src1_sel:DWORD
	v_add3_u32 v51, v51, v54, s61
	v_add3_u32 v50, v50, v55, s61
	v_and_b32_e32 v51, 0xffff0000, v51
	v_and_b32_e32 v50, 0xffff0000, v50
	v_or_b32_sdwa v51, v51, v52 dst_sel:DWORD dst_unused:UNUSED_PAD src0_sel:DWORD src1_sel:WORD_1
	v_or_b32_sdwa v50, v50, v53 dst_sel:DWORD dst_unused:UNUSED_PAD src0_sel:DWORD src1_sel:WORD_1
	ds_write_b64 v84, v[50:51] offset:1632
	v_mov_b32_e32 v50, 1.0
	s_and_b64 vcc, exec, s[4:5]
	v_mov_b32_e32 v52, 1.0
	s_cbranch_vccnz .LBB0_31
	v_mov_b32_e32 v52, v96
.LBB0_31:
	v_mov_b32_e32 v55, v48
	v_mov_b32_e32 v48, v47
	v_mov_b32_e32 v54, v46
	s_waitcnt vmcnt(0)
	v_pk_mul_f32 v[46:47], v[48:49], v[52:53] op_sel_hi:[1,0]
	v_pk_mul_f32 v[54:55], v[54:55], v[52:53] op_sel_hi:[1,0]
	v_and_b32_sdwa v51, v47, v89 dst_sel:DWORD dst_unused:UNUSED_PAD src0_sel:WORD_1 src1_sel:DWORD
	v_and_b32_sdwa v52, v46, v89 dst_sel:DWORD dst_unused:UNUSED_PAD src0_sel:WORD_1 src1_sel:DWORD
	v_and_b32_sdwa v48, v55, v89 dst_sel:DWORD dst_unused:UNUSED_PAD src0_sel:WORD_1 src1_sel:DWORD
	v_and_b32_sdwa v49, v54, v89 dst_sel:DWORD dst_unused:UNUSED_PAD src0_sel:WORD_1 src1_sel:DWORD
	v_add3_u32 v47, v47, v51, s61
	v_add3_u32 v46, v46, v52, s61
	v_add3_u32 v49, v54, v49, s61
	v_add3_u32 v48, v55, v48, s61
	v_and_b32_e32 v47, 0xffff0000, v47
	v_and_b32_e32 v46, 0xffff0000, v46
	v_or_b32_sdwa v47, v47, v48 dst_sel:DWORD dst_unused:UNUSED_PAD src0_sel:DWORD src1_sel:WORD_1
	v_or_b32_sdwa v46, v46, v49 dst_sel:DWORD dst_unused:UNUSED_PAD src0_sel:DWORD src1_sel:WORD_1
	s_and_b64 vcc, exec, s[4:5]
	ds_write_b64 v84, v[46:47] offset:2176
	s_cbranch_vccnz .LBB0_33
	v_mov_b32_e32 v50, v97
.LBB0_33:
	v_mov_b32_e32 v46, v42
	v_mov_b32_e32 v47, v44
	s_waitcnt vmcnt(0)
	v_pk_mul_f32 v[46:47], v[46:47], v[50:51] op_sel_hi:[1,0]
	v_mov_b32_e32 v44, v43
	v_pk_mul_f32 v[42:43], v[44:45], v[50:51] op_sel_hi:[1,0]
	v_and_b32_sdwa v44, v47, v89 dst_sel:DWORD dst_unused:UNUSED_PAD src0_sel:WORD_1 src1_sel:DWORD
	v_and_b32_sdwa v45, v46, v89 dst_sel:DWORD dst_unused:UNUSED_PAD src0_sel:WORD_1 src1_sel:DWORD
	v_add3_u32 v45, v46, v45, s61
	v_add3_u32 v44, v47, v44, s61
	v_and_b32_sdwa v46, v43, v89 dst_sel:DWORD dst_unused:UNUSED_PAD src0_sel:WORD_1 src1_sel:DWORD
	v_and_b32_sdwa v47, v42, v89 dst_sel:DWORD dst_unused:UNUSED_PAD src0_sel:WORD_1 src1_sel:DWORD
	v_add3_u32 v43, v43, v46, s61
	v_add3_u32 v42, v42, v47, s61
	v_and_b32_e32 v43, 0xffff0000, v43
	v_and_b32_e32 v42, 0xffff0000, v42
	v_or_b32_sdwa v43, v43, v44 dst_sel:DWORD dst_unused:UNUSED_PAD src0_sel:DWORD src1_sel:WORD_1
	v_or_b32_sdwa v42, v42, v45 dst_sel:DWORD dst_unused:UNUSED_PAD src0_sel:DWORD src1_sel:WORD_1
	ds_write_b64 v84, v[42:43] offset:2720
	v_mov_b32_e32 v42, 1.0
	s_and_b64 vcc, exec, s[4:5]
	v_mov_b32_e32 v44, 1.0
	s_cbranch_vccnz .LBB0_35
	v_mov_b32_e32 v44, v98
.LBB0_35:
	v_mov_b32_e32 v47, v40
	v_mov_b32_e32 v40, v39
	v_mov_b32_e32 v46, v38
	s_waitcnt vmcnt(0)
	v_pk_mul_f32 v[38:39], v[40:41], v[44:45] op_sel_hi:[1,0]
	v_pk_mul_f32 v[46:47], v[46:47], v[44:45] op_sel_hi:[1,0]
	v_and_b32_sdwa v43, v39, v89 dst_sel:DWORD dst_unused:UNUSED_PAD src0_sel:WORD_1 src1_sel:DWORD
	v_and_b32_sdwa v44, v38, v89 dst_sel:DWORD dst_unused:UNUSED_PAD src0_sel:WORD_1 src1_sel:DWORD
	v_and_b32_sdwa v40, v47, v89 dst_sel:DWORD dst_unused:UNUSED_PAD src0_sel:WORD_1 src1_sel:DWORD
	v_and_b32_sdwa v41, v46, v89 dst_sel:DWORD dst_unused:UNUSED_PAD src0_sel:WORD_1 src1_sel:DWORD
	v_add3_u32 v39, v39, v43, s61
	v_add3_u32 v38, v38, v44, s61
	v_add3_u32 v41, v46, v41, s61
	v_add3_u32 v40, v47, v40, s61
	v_and_b32_e32 v39, 0xffff0000, v39
	v_and_b32_e32 v38, 0xffff0000, v38
	v_or_b32_sdwa v39, v39, v40 dst_sel:DWORD dst_unused:UNUSED_PAD src0_sel:DWORD src1_sel:WORD_1
	v_or_b32_sdwa v38, v38, v41 dst_sel:DWORD dst_unused:UNUSED_PAD src0_sel:DWORD src1_sel:WORD_1
	s_and_b64 vcc, exec, s[4:5]
	ds_write_b64 v84, v[38:39] offset:3264
	s_cbranch_vccnz .LBB0_37
	v_mov_b32_e32 v42, v99
; #define LAS __attribute__((address_space(3)))
; __device__ __forceinline__ unsigned pk2(float lo, float hi) { return f2bf(lo) | (f2bf(hi) << 16); }
; __device__ __forceinline__ void p0_transpose_item(const float* W, int K, int N, bf16* WT, LAS float* scr_f, int item, int lane, const float* kscale = nullptr) {
;     ...
;     for (int i = 0; i < 16; ++i) { const float sc = kscale ? kscale[k0 + 4 * i + (lane >> 4)] : 1.0f;
;         *(LAS v2u*)(scr + (4 * i + (lane >> 4)) * 68 + (lane & 15) * 4) = (v2u){pk2(v[i].x * sc, v[i].y * sc), pk2(v[i].z * sc, v[i].w * sc)}; }
.LBB0_37:
	v_mov_b32_e32 v38, v34
	v_mov_b32_e32 v39, v36
	s_waitcnt vmcnt(0)
	v_pk_mul_f32 v[38:39], v[38:39], v[42:43] op_sel_hi:[1,0]
	v_mov_b32_e32 v36, v35
	v_pk_mul_f32 v[34:35], v[36:37], v[42:43] op_sel_hi:[1,0]
	v_and_b32_sdwa v36, v39, v89 dst_sel:DWORD dst_unused:UNUSED_PAD src0_sel:WORD_1 src1_sel:DWORD
	v_and_b32_sdwa v37, v38, v89 dst_sel:DWORD dst_unused:UNUSED_PAD src0_sel:WORD_1 src1_sel:DWORD
	v_add3_u32 v37, v38, v37, s61
	v_add3_u32 v36, v39, v36, s61
	v_and_b32_sdwa v38, v35, v89 dst_sel:DWORD dst_unused:UNUSED_PAD src0_sel:WORD_1 src1_sel:DWORD
	v_and_b32_sdwa v39, v34, v89 dst_sel:DWORD dst_unused:UNUSED_PAD src0_sel:WORD_1 src1_sel:DWORD
	v_add3_u32 v35, v35, v38, s61
	v_add3_u32 v34, v34, v39, s61
	v_and_b32_e32 v35, 0xffff0000, v35
	v_and_b32_e32 v34, 0xffff0000, v34
	v_or_b32_sdwa v35, v35, v36 dst_sel:DWORD dst_unused:UNUSED_PAD src0_sel:DWORD src1_sel:WORD_1
	v_or_b32_sdwa v34, v34, v37 dst_sel:DWORD dst_unused:UNUSED_PAD src0_sel:DWORD src1_sel:WORD_1
	ds_write_b64 v84, v[34:35] offset:3808
	v_mov_b32_e32 v34, 1.0
	s_and_b64 vcc, exec, s[4:5]
	v_mov_b32_e32 v36, 1.0
	s_cbranch_vccnz .LBB0_39
	v_mov_b32_e32 v36, v100
.LBB0_39:
	v_mov_b32_e32 v39, v32
	v_mov_b32_e32 v32, v31
	v_mov_b32_e32 v38, v30
	s_waitcnt vmcnt(0)
	v_pk_mul_f32 v[30:31], v[32:33], v[36:37] op_sel_hi:[1,0]
	v_pk_mul_f32 v[38:39], v[38:39], v[36:37] op_sel_hi:[1,0]
	v_and_b32_sdwa v35, v31, v89 dst_sel:DWORD dst_unused:UNUSED_PAD src0_sel:WORD_1 src1_sel:DWORD
	v_and_b32_sdwa v36, v30, v89 dst_sel:DWORD dst_unused:UNUSED_PAD src0_sel:WORD_1 src1_sel:DWORD
	v_and_b32_sdwa v32, v39, v89 dst_sel:DWORD dst_unused:UNUSED_PAD src0_sel:WORD_1 src1_sel:DWORD
	v_and_b32_sdwa v33, v38, v89 dst_sel:DWORD dst_unused:UNUSED_PAD src0_sel:WORD_1 src1_sel:DWORD
	v_add3_u32 v31, v31, v35, s61
	v_add3_u32 v30, v30, v36, s61
	v_add3_u32 v33, v38, v33, s61
	v_add3_u32 v32, v39, v32, s61
	v_and_b32_e32 v31, 0xffff0000, v31
	v_and_b32_e32 v30, 0xffff0000, v30
	v_or_b32_sdwa v31, v31, v32 dst_sel:DWORD dst_unused:UNUSED_PAD src0_sel:DWORD src1_sel:WORD_1
	v_or_b32_sdwa v30, v30, v33 dst_sel:DWORD dst_unused:UNUSED_PAD src0_sel:DWORD src1_sel:WORD_1
	s_and_b64 vcc, exec, s[4:5]
	ds_write_b64 v84, v[30:31] offset:4352
	s_cbranch_vccnz .LBB0_41
	v_mov_b32_e32 v34, v101
.LBB0_41:
	v_mov_b32_e32 v30, v26
	v_mov_b32_e32 v31, v28
	s_waitcnt vmcnt(0)
	v_pk_mul_f32 v[30:31], v[30:31], v[34:35] op_sel_hi:[1,0]
	v_mov_b32_e32 v28, v27
	v_pk_mul_f32 v[26:27], v[28:29], v[34:35] op_sel_hi:[1,0]
	v_and_b32_sdwa v28, v31, v89 dst_sel:DWORD dst_unused:UNUSED_PAD src0_sel:WORD_1 src1_sel:DWORD
	v_and_b32_sdwa v29, v30, v89 dst_sel:DWORD dst_unused:UNUSED_PAD src0_sel:WORD_1 src1_sel:DWORD
	v_add3_u32 v29, v30, v29, s61
	v_add3_u32 v28, v31, v28, s61
	v_and_b32_sdwa v30, v27, v89 dst_sel:DWORD dst_unused:UNUSED_PAD src0_sel:WORD_1 src1_sel:DWORD
	v_and_b32_sdwa v31, v26, v89 dst_sel:DWORD dst_unused:UNUSED_PAD src0_sel:WORD_1 src1_sel:DWORD
	v_add3_u32 v27, v27, v30, s61
	v_add3_u32 v26, v26, v31, s61
	v_and_b32_e32 v27, 0xffff0000, v27
	v_and_b32_e32 v26, 0xffff0000, v26
	v_or_b32_sdwa v27, v27, v28 dst_sel:DWORD dst_unused:UNUSED_PAD src0_sel:DWORD src1_sel:WORD_1
	v_or_b32_sdwa v26, v26, v29 dst_sel:DWORD dst_unused:UNUSED_PAD src0_sel:DWORD src1_sel:WORD_1
	ds_write_b64 v84, v[26:27] offset:4896
	v_mov_b32_e32 v26, 1.0
	s_and_b64 vcc, exec, s[4:5]
	v_mov_b32_e32 v28, 1.0
	s_cbranch_vccnz .LBB0_43
	v_mov_b32_e32 v28, v102
.LBB0_43:
	v_mov_b32_e32 v31, v24
	v_mov_b32_e32 v24, v23
	v_mov_b32_e32 v30, v22
	s_waitcnt vmcnt(0)
	v_pk_mul_f32 v[22:23], v[24:25], v[28:29] op_sel_hi:[1,0]
	v_pk_mul_f32 v[30:31], v[30:31], v[28:29] op_sel_hi:[1,0]
	v_and_b32_sdwa v27, v23, v89 dst_sel:DWORD dst_unused:UNUSED_PAD src0_sel:WORD_1 src1_sel:DWORD
	v_and_b32_sdwa v28, v22, v89 dst_sel:DWORD dst_unused:UNUSED_PAD src0_sel:WORD_1 src1_sel:DWORD
	v_and_b32_sdwa v24, v31, v89 dst_sel:DWORD dst_unused:UNUSED_PAD src0_sel:WORD_1 src1_sel:DWORD
	v_and_b32_sdwa v25, v30, v89 dst_sel:DWORD dst_unused:UNUSED_PAD src0_sel:WORD_1 src1_sel:DWORD
	v_add3_u32 v23, v23, v27, s61
	v_add3_u32 v22, v22, v28, s61
	v_add3_u32 v25, v30, v25, s61
	v_add3_u32 v24, v31, v24, s61
	v_and_b32_e32 v23, 0xffff0000, v23
	v_and_b32_e32 v22, 0xffff0000, v22
	v_or_b32_sdwa v23, v23, v24 dst_sel:DWORD dst_unused:UNUSED_PAD src0_sel:DWORD src1_sel:WORD_1
	v_or_b32_sdwa v22, v22, v25 dst_sel:DWORD dst_unused:UNUSED_PAD src0_sel:DWORD src1_sel:WORD_1
	s_and_b64 vcc, exec, s[4:5]
	ds_write_b64 v84, v[22:23] offset:5440
	s_cbranch_vccnz .LBB0_45
	v_mov_b32_e32 v26, v103
; #define LAS __attribute__((address_space(3)))
; __device__ __forceinline__ unsigned pk2(float lo, float hi) { return f2bf(lo) | (f2bf(hi) << 16); }
; __device__ __forceinline__ void p0_transpose_item(const float* W, int K, int N, bf16* WT, LAS float* scr_f, int item, int lane, const float* kscale = nullptr) {
;     ...
;     for (int i = 0; i < 16; ++i) { const float sc = kscale ? kscale[k0 + 4 * i + (lane >> 4)] : 1.0f;
;         *(LAS v2u*)(scr + (4 * i + (lane >> 4)) * 68 + (lane & 15) * 4) = (v2u){pk2(v[i].x * sc, v[i].y * sc), pk2(v[i].z * sc, v[i].w * sc)}; }
.LBB0_45:
	v_mov_b32_e32 v22, v18
	v_mov_b32_e32 v23, v20
	s_waitcnt vmcnt(0)
	v_pk_mul_f32 v[22:23], v[22:23], v[26:27] op_sel_hi:[1,0]
	v_mov_b32_e32 v20, v19
	v_pk_mul_f32 v[18:19], v[20:21], v[26:27] op_sel_hi:[1,0]
	v_and_b32_sdwa v20, v23, v89 dst_sel:DWORD dst_unused:UNUSED_PAD src0_sel:WORD_1 src1_sel:DWORD
	v_and_b32_sdwa v21, v22, v89 dst_sel:DWORD dst_unused:UNUSED_PAD src0_sel:WORD_1 src1_sel:DWORD
	v_add3_u32 v21, v22, v21, s61
	v_add3_u32 v20, v23, v20, s61
	v_and_b32_sdwa v22, v19, v89 dst_sel:DWORD dst_unused:UNUSED_PAD src0_sel:WORD_1 src1_sel:DWORD
	v_and_b32_sdwa v23, v18, v89 dst_sel:DWORD dst_unused:UNUSED_PAD src0_sel:WORD_1 src1_sel:DWORD
	v_add3_u32 v19, v19, v22, s61
	v_add3_u32 v18, v18, v23, s61
	v_and_b32_e32 v19, 0xffff0000, v19
	v_and_b32_e32 v18, 0xffff0000, v18
	v_or_b32_sdwa v19, v19, v20 dst_sel:DWORD dst_unused:UNUSED_PAD src0_sel:DWORD src1_sel:WORD_1
	v_or_b32_sdwa v18, v18, v21 dst_sel:DWORD dst_unused:UNUSED_PAD src0_sel:DWORD src1_sel:WORD_1
	ds_write_b64 v84, v[18:19] offset:5984
	v_mov_b32_e32 v18, 1.0
	s_and_b64 vcc, exec, s[4:5]
	v_mov_b32_e32 v20, 1.0
	s_cbranch_vccnz .LBB0_47
	v_mov_b32_e32 v20, v104
.LBB0_47:
	v_mov_b32_e32 v23, v16
	v_mov_b32_e32 v16, v15
	v_mov_b32_e32 v22, v14
	s_waitcnt vmcnt(0)
	v_pk_mul_f32 v[14:15], v[16:17], v[20:21] op_sel_hi:[1,0]
	v_pk_mul_f32 v[22:23], v[22:23], v[20:21] op_sel_hi:[1,0]
	v_and_b32_sdwa v19, v15, v89 dst_sel:DWORD dst_unused:UNUSED_PAD src0_sel:WORD_1 src1_sel:DWORD
	v_and_b32_sdwa v20, v14, v89 dst_sel:DWORD dst_unused:UNUSED_PAD src0_sel:WORD_1 src1_sel:DWORD
	v_and_b32_sdwa v16, v23, v89 dst_sel:DWORD dst_unused:UNUSED_PAD src0_sel:WORD_1 src1_sel:DWORD
	v_and_b32_sdwa v17, v22, v89 dst_sel:DWORD dst_unused:UNUSED_PAD src0_sel:WORD_1 src1_sel:DWORD
	v_add3_u32 v15, v15, v19, s61
	v_add3_u32 v14, v14, v20, s61
	v_add3_u32 v17, v22, v17, s61
	v_add3_u32 v16, v23, v16, s61
	v_and_b32_e32 v15, 0xffff0000, v15
	v_and_b32_e32 v14, 0xffff0000, v14
	v_or_b32_sdwa v15, v15, v16 dst_sel:DWORD dst_unused:UNUSED_PAD src0_sel:DWORD src1_sel:WORD_1
	v_or_b32_sdwa v14, v14, v17 dst_sel:DWORD dst_unused:UNUSED_PAD src0_sel:DWORD src1_sel:WORD_1
	s_and_b64 vcc, exec, s[4:5]
	ds_write_b64 v84, v[14:15] offset:6528
	s_cbranch_vccnz .LBB0_49
	v_mov_b32_e32 v18, v105
.LBB0_49:
	v_mov_b32_e32 v14, v10
	v_mov_b32_e32 v15, v12
	s_waitcnt vmcnt(0)
	v_pk_mul_f32 v[14:15], v[14:15], v[18:19] op_sel_hi:[1,0]
	v_mov_b32_e32 v12, v11
	v_pk_mul_f32 v[10:11], v[12:13], v[18:19] op_sel_hi:[1,0]
	v_and_b32_sdwa v12, v15, v89 dst_sel:DWORD dst_unused:UNUSED_PAD src0_sel:WORD_1 src1_sel:DWORD
	v_and_b32_sdwa v13, v14, v89 dst_sel:DWORD dst_unused:UNUSED_PAD src0_sel:WORD_1 src1_sel:DWORD
	v_add3_u32 v13, v14, v13, s61
	v_add3_u32 v12, v15, v12, s61
	v_and_b32_sdwa v14, v11, v89 dst_sel:DWORD dst_unused:UNUSED_PAD src0_sel:WORD_1 src1_sel:DWORD
	v_and_b32_sdwa v15, v10, v89 dst_sel:DWORD dst_unused:UNUSED_PAD src0_sel:WORD_1 src1_sel:DWORD
	v_add3_u32 v11, v11, v14, s61
	v_add3_u32 v10, v10, v15, s61
	v_and_b32_e32 v11, 0xffff0000, v11
	v_and_b32_e32 v10, 0xffff0000, v10
	v_or_b32_sdwa v11, v11, v12 dst_sel:DWORD dst_unused:UNUSED_PAD src0_sel:DWORD src1_sel:WORD_1
	v_or_b32_sdwa v10, v10, v13 dst_sel:DWORD dst_unused:UNUSED_PAD src0_sel:DWORD src1_sel:WORD_1
	ds_write_b64 v84, v[10:11] offset:7072
	v_mov_b32_e32 v10, 1.0
	s_and_b64 vcc, exec, s[4:5]
	v_mov_b32_e32 v12, 1.0
	s_cbranch_vccnz .LBB0_51
	v_mov_b32_e32 v12, v106
.LBB0_51:
	v_mov_b32_e32 v15, v8
	v_mov_b32_e32 v8, v7
	v_mov_b32_e32 v14, v6
	s_waitcnt vmcnt(0)
	v_pk_mul_f32 v[6:7], v[8:9], v[12:13] op_sel_hi:[1,0]
	v_pk_mul_f32 v[14:15], v[14:15], v[12:13] op_sel_hi:[1,0]
	v_and_b32_sdwa v11, v7, v89 dst_sel:DWORD dst_unused:UNUSED_PAD src0_sel:WORD_1 src1_sel:DWORD
	v_and_b32_sdwa v12, v6, v89 dst_sel:DWORD dst_unused:UNUSED_PAD src0_sel:WORD_1 src1_sel:DWORD
	v_and_b32_sdwa v8, v15, v89 dst_sel:DWORD dst_unused:UNUSED_PAD src0_sel:WORD_1 src1_sel:DWORD
	v_and_b32_sdwa v9, v14, v89 dst_sel:DWORD dst_unused:UNUSED_PAD src0_sel:WORD_1 src1_sel:DWORD
	v_add3_u32 v7, v7, v11, s61
	v_add3_u32 v6, v6, v12, s61
	v_add3_u32 v9, v14, v9, s61
	v_add3_u32 v8, v15, v8, s61
	v_and_b32_e32 v7, 0xffff0000, v7
	v_and_b32_e32 v6, 0xffff0000, v6
	v_or_b32_sdwa v7, v7, v8 dst_sel:DWORD dst_unused:UNUSED_PAD src0_sel:DWORD src1_sel:WORD_1
	v_or_b32_sdwa v6, v6, v9 dst_sel:DWORD dst_unused:UNUSED_PAD src0_sel:DWORD src1_sel:WORD_1
	s_and_b64 vcc, exec, s[4:5]
	ds_write_b64 v84, v[6:7] offset:7616
	s_cbranch_vccnz .LBB0_12
	v_mov_b32_e32 v10, v107
	s_branch .LBB0_12
